# P0 weight transpose (w_in path): 8 W + 8 gain loads in flight per iteration instead of one serialized round trip per element
# speedup vs baseline: 1.0182x; 1.0109x over previous
; __device__ __forceinline__ void transpose_item(const float* W, int ldw, int ncol0, bf16_t* WT, int row_off, const float* kscale, LAS float* scr, int kb, int nb, int lane) {
;     const int k0 = 64 * kb, n0 = 32 * nb;
; #pragma unroll 8
;     for (int i = 0; i < 32; ++i) { const int kk = 2 * i + (lane >> 5); float v = W[(size_t)(k0 + kk) * ldw + ncol0 + n0 + (lane & 31)]; if (kscale) v *= kscale[k0 + kk]; scr[kk * 33 + (lane & 31)] = v; }
; __device__ __forceinline__ void phase0(const Args& a, LAS unsigned char* lds, int tid, int lane, int wave) {
;     ...
;         if (it < I_IN) transpose_item(a.w_in, 6144, 0, Wt, 0, a.norm_w, scr, it / 192, it % 192, lane);
.LBB0_69:
	s_and_b64 vcc, exec, s[0:1]
	s_cbranch_vccz .LBB0_64
	s_mul_hi_i32 s0, s22, 0x2aaaaaab
	s_lshr_b32 s1, s0, 31
	s_ashr_i32 s0, s0, 5
	s_add_i32 s0, s0, s1
	s_mul_i32 s1, s0, 0xc0
	s_sub_i32 s1, s22, s1
	s_lshl_b32 s10, s1, 5
	s_ashr_i32 s11, s10, 31
	s_lshl_b32 s12, s0, 6
	s_lshl_b64 s[0:1], s[10:11], 2
	v_or_b32_e32 v3, s12, v45
	v_mov_b64_e32 v[32:33], s[0:1]
	v_mad_i64_i32 v[14:15], s[0:1], v3, s21, v[32:33]
	v_or_b32_e32 v3, s12, v46
	v_mad_i64_i32 v[18:19], s[0:1], v3, s21, v[32:33]
	v_or_b32_e32 v3, s12, v47
	v_mad_i64_i32 v[20:21], s[0:1], v3, s21, v[32:33]
	v_or_b32_e32 v3, s12, v48
	v_mad_i64_i32 v[22:23], s[0:1], v3, s21, v[32:33]
	v_or_b32_e32 v3, s12, v49
	v_mad_i64_i32 v[24:25], s[0:1], v3, s21, v[32:33]
	v_or_b32_e32 v3, s12, v50
	s_ashr_i32 s13, s12, 31
	v_mad_i64_i32 v[26:27], s[0:1], v3, s21, v[32:33]
	v_or_b32_e32 v3, s12, v51
	v_or_b32_e32 v34, s12, v0
	v_mov_b32_e32 v17, s13
	v_or_b32_e32 v16, s12, v0
	v_mad_i64_i32 v[28:29], s[0:1], v3, s21, v[32:33]
	v_ashrrev_i32_e32 v35, 31, v34
	v_mad_i64_i32 v[32:33], s[0:1], v34, s21, v[32:33]
	v_lshl_add_u64 v[14:15], v[12:13], 0, v[14:15]
	v_lshlrev_b64 v[16:17], 2, v[16:17]
	v_lshl_add_u64 v[18:19], v[12:13], 0, v[18:19]
	v_lshl_add_u64 v[20:21], v[12:13], 0, v[20:21]
	v_lshl_add_u64 v[22:23], v[12:13], 0, v[22:23]
	v_lshl_add_u64 v[24:25], v[12:13], 0, v[24:25]
	v_lshl_add_u64 v[26:27], v[12:13], 0, v[26:27]
	v_lshl_add_u64 v[28:29], v[12:13], 0, v[28:29]
	v_lshlrev_b64 v[30:31], 2, v[34:35]
	v_lshl_add_u64 v[32:33], v[12:13], 0, v[32:33]
	s_mov_b64 s[14:15], 0
	s_mov_b64 s[16:17], s[38:39]
	v_mov_b32_e32 v3, v44
	s_and_b64 vcc, exec, s[8:9]
	s_cbranch_vccnz .Lp0_t72_fast
	s_branch .LBB0_72

; __device__ __forceinline__ void transpose_item(const float* W, int ldw, int ncol0, bf16_t* WT, int row_off, const float* kscale, LAS float* scr, int kb, int nb, int lane) {
;     ...
;     for (int i = 0; i < 32; ++i) { const int kk = 2 * i + (lane >> 5); float v = W[(size_t)(k0 + kk) * ldw + ncol0 + n0 + (lane & 31)]; if (kscale) v *= kscale[k0 + kk]; scr[kk * 33 + (lane & 31)] = v; }
.Lp0_t72_fast:
	v_lshl_add_u64 v[34:35], v[32:33], 0, s[14:15]
	global_load_dword v200, v[34:35], off
	v_lshl_add_u64 v[34:35], v[28:29], 0, s[14:15]
	global_load_dword v201, v[34:35], off
	v_lshl_add_u64 v[34:35], v[26:27], 0, s[14:15]
	global_load_dword v202, v[34:35], off
	v_lshl_add_u64 v[34:35], v[24:25], 0, s[14:15]
	global_load_dword v203, v[34:35], off
	v_lshl_add_u64 v[34:35], v[22:23], 0, s[14:15]
	global_load_dword v204, v[34:35], off
	v_lshl_add_u64 v[34:35], v[20:21], 0, s[14:15]
	global_load_dword v205, v[34:35], off
	v_lshl_add_u64 v[34:35], v[18:19], 0, s[14:15]
	global_load_dword v206, v[34:35], off
	v_lshl_add_u64 v[34:35], v[14:15], 0, s[14:15]
	global_load_dword v207, v[34:35], off
	v_lshl_add_u64 v[34:35], s[16:17], 0, v[30:31]
	global_load_dword v208, v[34:35], off
	v_lshl_add_u64 v[34:35], s[16:17], 0, v[16:17]
	global_load_dword v209, v[34:35], off offset:8
	global_load_dword v210, v[34:35], off offset:16
	global_load_dword v211, v[34:35], off offset:24
	global_load_dword v212, v[34:35], off offset:32
	global_load_dword v213, v[34:35], off offset:40
	global_load_dword v214, v[34:35], off offset:48
	global_load_dword v215, v[34:35], off offset:56
	s_waitcnt vmcnt(0)
	v_mul_f32_e32 v200, v200, v208
	v_mul_f32_e32 v201, v201, v209
	v_mul_f32_e32 v202, v202, v210
	v_mul_f32_e32 v203, v203, v211
	v_mul_f32_e32 v204, v204, v212
	v_mul_f32_e32 v205, v205, v213
	v_mul_f32_e32 v206, v206, v214
	v_mul_f32_e32 v207, v207, v215
	ds_write_b32 v3, v200
	ds_write_b32 v3, v201 offset:264
	ds_write_b32 v3, v202 offset:528
	ds_write_b32 v3, v203 offset:792
	ds_write_b32 v3, v204 offset:1056
	ds_write_b32 v3, v205 offset:1320
	ds_write_b32 v3, v206 offset:1584
	ds_write_b32 v3, v207 offset:1848
	s_add_u32 s14, s14, 0x60000
	s_addc_u32 s15, s15, 0
	s_add_u32 s16, s16, 64
	s_addc_u32 s17, s17, 0
	s_cmp_lg_u32 s14, 0x180000
	v_add_u32_e32 v3, 0x840, v3
	s_cbranch_scc1 .Lp0_t72_fast
	s_branch .LBB0_63
